# LDS-DMA hook (conv taps for trailing half, ssq partials for leading half) issued AFTER the segment's counted vmcnt(8) wait so the K-loop's in-flight accounting is untouched
# speedup vs baseline: 1.0098x; 1.0031x over previous
; #define PG8_STAGE(bufoff, gbase, voff) do { _Pragma("unroll") for (int _i = 0; _i < 2; ++_i) { \
;         const unsigned _m0 = ldsu + (unsigned)(bufoff) + ldsw + (unsigned)(_i * 8192); \
;         asm volatile("s_mov_b32 m0, %2\n\ts_nop 0\n\tglobal_load_lds_dwordx4 %0, %1" :: "v"((voff)[_i]), "s"((const char*)(gbase)), "s"(_m0) : "memory"); } } while (0)
; #define PG8_LDA(dst, b, h) do { _Pragma("unroll") for (int m = 0; m < 4; ++m) _Pragma("unroll") for (int k = 0; k < 2; ++k) dst[m][k] = *(const LAS bf16x8*)(lds + PG8_SA(b, h) + aoff + m * 2048 + k * 1024); } while (0)
; #define PG8_LDB(dst, b, h) do { _Pragma("unroll") for (int n = 0; n < 2; ++n) _Pragma("unroll") for (int k = 0; k < 2; ++k) dst[n][k] = *(const LAS bf16x8*)(lds + bbase[b][h] + n * 2048 + k * 1024); } while (0)
; #define PG8_WAIT_V(n) asm volatile("s_waitcnt vmcnt(" #n ")" ::: "memory")
; #define PG8_WAIT_L(n) asm volatile("s_waitcnt lgkmcnt(" #n ")" ::: "memory")
; #define PG8_BAR __builtin_amdgcn_s_barrier()
; #define PG8_SCHED __builtin_amdgcn_sched_barrier(0)
; template <class Epi>
; __device__ __forceinline__ void gemm_phase(LAS unsigned char* lds, const Gemm g, const StaticOrder& S, const Epi& E) {
;     ...
;         for (int t = 0; t < nt; t += 2) {
;             const bool last = (t == nt - 2);
;             const char* a2 = last ? nA : cA + (size_t)(t + 2) * kstep; const char* b2 = last ? nB : cB + (size_t)(t + 2) * kstep;
;             const char* a3 = a2 + kstep; const char* b3 = b2 + kstep;
;             const char* b1 = cB + (size_t)(t + 1) * kstep;
;             PG8_LDB(B0, 0, 0); PG8_SCHED; PG8_LDA(At, 0, 0); PG8_LDA(At2, 0, 1); PG8_STAGE(PG8_SB(1, 1), b1 + hstepB, voffB);
;             PG8_WAIT_V(8); PG8_WAIT_L(0); PG8_BAR; PG8_MMA2B(0, At, At2, B0); PG8_BAR; PG8_SCHED;
;             PG8_LDB(B0, 0, 1); PG8_STAGE(PG8_SB(0, 0), b2, voffB); PG8_STAGE(PG8_SA(0, 0), a2, voffA); PG8_STAGE(PG8_SA(0, 1), a2 + hstepA, voffA);
;             PG8_WAIT_V(8); PG8_WAIT_L(0); PG8_BAR; PG8_MMA2B(1, At, At2, B0); PG8_BAR; PG8_SCHED;
.LBB0_1027:
	ds_read_b128 v[68:71], v220
	ds_read_b128 v[84:87], v220 offset:1024
	ds_read_b128 v[88:91], v220 offset:2048
	ds_read_b128 v[92:95], v220 offset:3072
	s_add_u32 s12, s10, 0x100
	s_addc_u32 s13, s11, 0
	s_cmp_eq_u32 s69, 12
	s_cselect_b32 s14, s97, vcc_hi
	s_cselect_b32 s15, s7, s68
	s_cselect_b32 s84, vcc_lo, s12
	s_cselect_b32 s85, s39, s13
	s_add_u32 s16, s14, 0x80
	s_addc_u32 s17, s15, 0
	ds_read_b128 v[96:99], v221
	ds_read_b128 v[100:103], v221 offset:1024
	ds_read_b128 v[152:155], v221 offset:2048
	ds_read_b128 v[156:159], v221 offset:3072
	ds_read_b128 v[166:169], v221 offset:4096
	ds_read_b128 v[178:181], v221 offset:5120
	ds_read_b128 v[182:185], v221 offset:6144
	ds_read_b128 v[186:189], v221 offset:7168
	ds_read_b128 v[190:193], v221 offset:16384
	ds_read_b128 v[194:197], v221 offset:17408
	ds_read_b128 v[198:201], v221 offset:18432
	ds_read_b128 v[202:205], v221 offset:19456
	ds_read_b128 v[226:229], v221 offset:20480
	ds_read_b128 v[230:233], v221 offset:21504
	ds_read_b128 v[234:237], v221 offset:22528
	ds_read_b128 v[238:241], v221 offset:23552
	s_add_u32 s10, s10, 0x40080
	s_addc_u32 s11, s11, 0
	s_mov_b32 m0, s58
	s_nop 0
	global_load_lds_dwordx4 v217, s[10:11]
	s_mov_b32 m0, s60
	s_nop 0
	global_load_lds_dwordx4 v219, s[10:11]
	s_waitcnt vmcnt(8)
	s_waitcnt lgkmcnt(0)
	s_barrier
	v_mfma_f32_16x16x32_bf16 v[80:83], v[68:71], v[96:99], v[80:83]
	v_mfma_f32_16x16x32_bf16 v[76:79], v[88:91], v[96:99], v[76:79]
	v_mfma_f32_16x16x32_bf16 v[148:151], v[68:71], v[152:155], v[148:151]
	v_mfma_f32_16x16x32_bf16 v[52:55], v[88:91], v[152:155], v[52:55]
	v_mfma_f32_16x16x32_bf16 v[144:147], v[68:71], v[166:169], v[144:147]
	v_mfma_f32_16x16x32_bf16 v[48:51], v[88:91], v[166:169], v[48:51]
	v_mfma_f32_16x16x32_bf16 v[136:139], v[68:71], v[182:185], v[136:139]
	v_mfma_f32_16x16x32_bf16 v[40:43], v[88:91], v[182:185], v[40:43]
	v_mfma_f32_16x16x32_bf16 v[124:127], v[68:71], v[190:193], v[124:127]
	v_mfma_f32_16x16x32_bf16 v[28:31], v[88:91], v[190:193], v[28:31]
	v_mfma_f32_16x16x32_bf16 v[120:123], v[68:71], v[198:201], v[120:123]
	v_mfma_f32_16x16x32_bf16 v[24:27], v[88:91], v[198:201], v[24:27]
	v_mfma_f32_16x16x32_bf16 v[112:115], v[68:71], v[226:229], v[112:115]
	v_mfma_f32_16x16x32_bf16 v[16:19], v[88:91], v[226:229], v[16:19]
	v_mfma_f32_16x16x32_bf16 v[64:67], v[68:71], v[234:237], v[64:67]
	v_mfma_f32_16x16x32_bf16 v[4:7], v[88:91], v[234:237], v[4:7]
	v_mfma_f32_16x16x32_bf16 v[80:83], v[84:87], v[100:103], v[80:83]
	v_mfma_f32_16x16x32_bf16 v[76:79], v[92:95], v[100:103], v[76:79]
	v_mfma_f32_16x16x32_bf16 v[148:151], v[84:87], v[156:159], v[148:151]
	v_mfma_f32_16x16x32_bf16 v[52:55], v[92:95], v[156:159], v[52:55]
	v_mfma_f32_16x16x32_bf16 v[144:147], v[84:87], v[178:181], v[144:147]
	v_mfma_f32_16x16x32_bf16 v[48:51], v[92:95], v[178:181], v[48:51]
	v_mfma_f32_16x16x32_bf16 v[136:139], v[84:87], v[186:189], v[136:139]
	v_mfma_f32_16x16x32_bf16 v[40:43], v[92:95], v[186:189], v[40:43]
	v_mfma_f32_16x16x32_bf16 v[124:127], v[84:87], v[194:197], v[124:127]
	v_mfma_f32_16x16x32_bf16 v[28:31], v[92:95], v[194:197], v[28:31]
	v_mfma_f32_16x16x32_bf16 v[120:123], v[84:87], v[202:205], v[120:123]
	v_mfma_f32_16x16x32_bf16 v[24:27], v[92:95], v[202:205], v[24:27]
	v_mfma_f32_16x16x32_bf16 v[112:115], v[84:87], v[230:233], v[112:115]
	v_mfma_f32_16x16x32_bf16 v[16:19], v[92:95], v[230:233], v[16:19]
	v_mfma_f32_16x16x32_bf16 v[64:67], v[84:87], v[238:241], v[64:67]
	v_mfma_f32_16x16x32_bf16 v[4:7], v[92:95], v[238:241], v[4:7]
	s_barrier
	ds_read_b128 v[68:71], v222
	ds_read_b128 v[84:87], v222 offset:1024
	ds_read_b128 v[88:91], v222 offset:2048
	ds_read_b128 v[92:95], v222 offset:3072
	s_mov_b32 m0, s48
	s_nop 0
	global_load_lds_dwordx4 v217, s[84:85]
	s_mov_b32 m0, s49
	s_nop 0
	global_load_lds_dwordx4 v219, s[84:85]
	s_mov_b32 m0, s47
	s_nop 0
	global_load_lds_dwordx4 v216, s[14:15]
	s_mov_b32 m0, s50
	s_nop 0
	global_load_lds_dwordx4 v218, s[14:15]
	s_add_u32 s10, s14, 0x40000
	s_addc_u32 s11, s15, 0
	s_mov_b32 m0, s51
	s_nop 0
	global_load_lds_dwordx4 v216, s[10:11]
	s_mov_b32 m0, s52
	s_nop 0
	global_load_lds_dwordx4 v218, s[10:11]
	s_waitcnt vmcnt(8)
	s_waitcnt lgkmcnt(0)
	s_barrier
	v_mfma_f32_16x16x32_bf16 v[72:75], v[68:71], v[96:99], v[72:75]
	v_mfma_f32_16x16x32_bf16 v[56:59], v[88:91], v[96:99], v[56:59]
	v_mfma_f32_16x16x32_bf16 v[44:47], v[88:91], v[152:155], v[44:47]
	v_mfma_f32_16x16x32_bf16 v[36:39], v[88:91], v[166:169], v[36:39]
	v_mfma_f32_16x16x32_bf16 v[128:131], v[68:71], v[182:185], v[128:131]
	v_mfma_f32_16x16x32_bf16 v[32:35], v[88:91], v[182:185], v[32:35]
	v_mfma_f32_16x16x32_bf16 v[116:119], v[68:71], v[190:193], v[116:119]
	v_mfma_f32_16x16x32_bf16 v[20:23], v[88:91], v[190:193], v[20:23]
	v_mfma_f32_16x16x32_bf16 v[108:111], v[68:71], v[198:201], v[108:111]
	v_mfma_f32_16x16x32_bf16 v[12:15], v[88:91], v[198:201], v[12:15]
	v_mfma_f32_16x16x32_bf16 v[104:107], v[68:71], v[226:229], v[104:107]
	v_mfma_f32_16x16x32_bf16 v[8:11], v[88:91], v[226:229], v[8:11]
	v_mfma_f32_16x16x32_bf16 v[60:63], v[68:71], v[234:237], v[60:63]
	v_mfma_f32_16x16x32_bf16 v[0:3], v[88:91], v[234:237], v[0:3]
	v_mfma_f32_16x16x32_bf16 v[72:75], v[84:87], v[100:103], v[72:75]
	v_mfma_f32_16x16x32_bf16 v[56:59], v[92:95], v[100:103], v[56:59]
	v_mfma_f32_16x16x32_bf16 v[96:99], v[68:71], v[152:155], v[140:143]
	v_mfma_f32_16x16x32_bf16 v[44:47], v[92:95], v[156:159], v[44:47]
	v_mfma_f32_16x16x32_bf16 v[100:103], v[68:71], v[166:169], v[132:135]
	v_mfma_f32_16x16x32_bf16 v[36:39], v[92:95], v[178:181], v[36:39]
	v_mfma_f32_16x16x32_bf16 v[128:131], v[84:87], v[186:189], v[128:131]
	v_mfma_f32_16x16x32_bf16 v[32:35], v[92:95], v[186:189], v[32:35]
	v_mfma_f32_16x16x32_bf16 v[116:119], v[84:87], v[194:197], v[116:119]
	v_mfma_f32_16x16x32_bf16 v[20:23], v[92:95], v[194:197], v[20:23]
	v_mfma_f32_16x16x32_bf16 v[108:111], v[84:87], v[202:205], v[108:111]
	v_mfma_f32_16x16x32_bf16 v[12:15], v[92:95], v[202:205], v[12:15]
	v_mfma_f32_16x16x32_bf16 v[104:107], v[84:87], v[230:233], v[104:107]
	v_mfma_f32_16x16x32_bf16 v[8:11], v[92:95], v[230:233], v[8:11]
	v_mfma_f32_16x16x32_bf16 v[60:63], v[84:87], v[238:241], v[60:63]
	v_mfma_f32_16x16x32_bf16 v[0:3], v[92:95], v[238:241], v[0:3]
	v_mfma_f32_16x16x32_bf16 v[96:99], v[84:87], v[156:159], v[96:99]
	v_mfma_f32_16x16x32_bf16 v[100:103], v[84:87], v[178:181], v[100:103]
	s_barrier
; #define LAS __attribute__((address_space(3)))
; #define PG8_STAGE(bufoff, gbase, voff) do { _Pragma("unroll") for (int _i = 0; _i < 2; ++_i) { \
;         const unsigned _m0 = ldsu + (unsigned)(bufoff) + ldsw + (unsigned)(_i * 8192); \
;         asm volatile("s_mov_b32 m0, %2\n\ts_nop 0\n\tglobal_load_lds_dwordx4 %0, %1" :: "v"((voff)[_i]), "s"((const char*)(gbase)), "s"(_m0) : "memory"); } } while (0)
; #define PG8_LDA(dst, b, h) do { _Pragma("unroll") for (int m = 0; m < 4; ++m) _Pragma("unroll") for (int k = 0; k < 2; ++k) dst[m][k] = *(const LAS bf16x8*)(lds + PG8_SA(b, h) + aoff + m * 2048 + k * 1024); } while (0)
; #define PG8_LDB(dst, b, h) do { _Pragma("unroll") for (int n = 0; n < 2; ++n) _Pragma("unroll") for (int k = 0; k < 2; ++k) dst[n][k] = *(const LAS bf16x8*)(lds + bbase[b][h] + n * 2048 + k * 1024); } while (0)
; #define PG8_WAIT_V(n) asm volatile("s_waitcnt vmcnt(" #n ")" ::: "memory")
; #define PG8_WAIT_L(n) asm volatile("s_waitcnt lgkmcnt(" #n ")" ::: "memory")
; #define PG8_BAR __builtin_amdgcn_s_barrier()
; #define PG8_SCHED __builtin_amdgcn_sched_barrier(0)
; template <class Epi>
; __device__ __forceinline__ void gemm_phase(LAS unsigned char* lds, const Gemm g, const StaticOrder& S, const Epi& E) {
;     ...
;             PG8_LDB(B0, 1, 0); PG8_SCHED; PG8_LDA(At, 1, 0); PG8_LDA(At2, 1, 1); PG8_STAGE(PG8_SB(0, 1), b2 + hstepB, voffB);
;             PG8_WAIT_V(8); PG8_WAIT_L(0); PG8_BAR; PG8_MMA2B(0, At, At2, B0); PG8_BAR; PG8_SCHED;
;             PG8_LDB(B0, 1, 1); PG8_STAGE(PG8_SB(1, 0), b3, voffB); PG8_STAGE(PG8_SA(1, 0), a3, voffA); PG8_STAGE(PG8_SA(1, 1), a3 + hstepA, voffA);
;             PG8_WAIT_V(8); PG8_WAIT_L(0); PG8_BAR; PG8_MMA2B(1, At, At2, B0); PG8_BAR; PG8_SCHED;
;     __device__ __forceinline__ void operator()(f32x4 (&acc)[2][2][4][2], const Unit& u, int wr, int wc, int fr, int fq) const {
;     ...
;           else { const int which = t >> 6, j = (t & 63) * 4, bj = j >> 7, c = j & 127; const float* src = (which < 3 ? cw + (size_t)which * NUP : cb) + bj * DFF + u.pn * 128 + c;
;               *(LAS f32x4*)(cwL + which * 256 + j) = *(const f32x4*)src; } }
	ds_read_b128 v[68:71], v223
	ds_read_b128 v[84:87], v223 offset:1024
	ds_read_b128 v[88:91], v223 offset:2048
	ds_read_b128 v[92:95], v223 offset:3072
	ds_read_b128 v[132:135], v221 offset:32768
	ds_read_b128 v[140:143], v221 offset:33792
	ds_read_b128 v[152:155], v221 offset:34816
	ds_read_b128 v[156:159], v221 offset:35840
	ds_read_b128 v[166:169], v221 offset:36864
	ds_read_b128 v[178:181], v221 offset:37888
	ds_read_b128 v[182:185], v221 offset:38912
	ds_read_b128 v[186:189], v221 offset:39936
	ds_read_b128 v[190:193], v221 offset:49152
	ds_read_b128 v[194:197], v221 offset:50176
	ds_read_b128 v[198:201], v221 offset:51200
	ds_read_b128 v[202:205], v221 offset:52224
	ds_read_b128 v[226:229], v221 offset:53248
	ds_read_b128 v[230:233], v221 offset:54272
	ds_read_b128 v[234:237], v221 offset:55296
	ds_read_b128 v[238:241], v221 offset:56320
	s_add_u32 s10, s84, 0x40000
	s_addc_u32 s11, s85, 0
	s_mov_b32 m0, s53
	s_nop 0
	global_load_lds_dwordx4 v217, s[10:11]
	s_mov_b32 m0, s54
	s_nop 0
	global_load_lds_dwordx4 v219, s[10:11]
	s_waitcnt vmcnt(8)
	s_waitcnt lgkmcnt(0)
	s_barrier
	v_mfma_f32_16x16x32_bf16 v[80:83], v[68:71], v[132:135], v[80:83]
	v_mfma_f32_16x16x32_bf16 v[76:79], v[88:91], v[132:135], v[76:79]
	v_mfma_f32_16x16x32_bf16 v[148:151], v[68:71], v[152:155], v[148:151]
	v_mfma_f32_16x16x32_bf16 v[52:55], v[88:91], v[152:155], v[52:55]
	v_mfma_f32_16x16x32_bf16 v[144:147], v[68:71], v[166:169], v[144:147]
	v_mfma_f32_16x16x32_bf16 v[48:51], v[88:91], v[166:169], v[48:51]
	v_mfma_f32_16x16x32_bf16 v[136:139], v[68:71], v[182:185], v[136:139]
	v_mfma_f32_16x16x32_bf16 v[40:43], v[88:91], v[182:185], v[40:43]
	v_mfma_f32_16x16x32_bf16 v[124:127], v[68:71], v[190:193], v[124:127]
	v_mfma_f32_16x16x32_bf16 v[28:31], v[88:91], v[190:193], v[28:31]
	v_mfma_f32_16x16x32_bf16 v[120:123], v[68:71], v[198:201], v[120:123]
	v_mfma_f32_16x16x32_bf16 v[24:27], v[88:91], v[198:201], v[24:27]
	v_mfma_f32_16x16x32_bf16 v[112:115], v[68:71], v[226:229], v[112:115]
	v_mfma_f32_16x16x32_bf16 v[16:19], v[88:91], v[226:229], v[16:19]
	v_mfma_f32_16x16x32_bf16 v[64:67], v[68:71], v[234:237], v[64:67]
	v_mfma_f32_16x16x32_bf16 v[4:7], v[88:91], v[234:237], v[4:7]
	v_mfma_f32_16x16x32_bf16 v[80:83], v[84:87], v[140:143], v[80:83]
	v_mfma_f32_16x16x32_bf16 v[76:79], v[92:95], v[140:143], v[76:79]
	v_mfma_f32_16x16x32_bf16 v[148:151], v[84:87], v[156:159], v[148:151]
	v_mfma_f32_16x16x32_bf16 v[52:55], v[92:95], v[156:159], v[52:55]
	v_mfma_f32_16x16x32_bf16 v[144:147], v[84:87], v[178:181], v[144:147]
	v_mfma_f32_16x16x32_bf16 v[48:51], v[92:95], v[178:181], v[48:51]
	v_mfma_f32_16x16x32_bf16 v[136:139], v[84:87], v[186:189], v[136:139]
	v_mfma_f32_16x16x32_bf16 v[40:43], v[92:95], v[186:189], v[40:43]
	v_mfma_f32_16x16x32_bf16 v[124:127], v[84:87], v[194:197], v[124:127]
	v_mfma_f32_16x16x32_bf16 v[28:31], v[92:95], v[194:197], v[28:31]
	v_mfma_f32_16x16x32_bf16 v[120:123], v[84:87], v[202:205], v[120:123]
	v_mfma_f32_16x16x32_bf16 v[24:27], v[92:95], v[202:205], v[24:27]
	v_mfma_f32_16x16x32_bf16 v[112:115], v[84:87], v[230:233], v[112:115]
	v_mfma_f32_16x16x32_bf16 v[16:19], v[92:95], v[230:233], v[16:19]
	v_mfma_f32_16x16x32_bf16 v[64:67], v[84:87], v[238:241], v[64:67]
	v_mfma_f32_16x16x32_bf16 v[4:7], v[92:95], v[238:241], v[4:7]
	s_barrier
	s_add_u32 s10, s84, 0x80
	ds_read_b128 v[68:71], v224
	ds_read_b128 v[84:87], v224 offset:1024
	ds_read_b128 v[88:91], v224 offset:2048
	ds_read_b128 v[92:95], v224 offset:3072
	s_addc_u32 s11, s85, 0
	s_mov_b32 m0, s88
	s_nop 0
	global_load_lds_dwordx4 v217, s[10:11]
	s_mov_b32 m0, s89
	s_nop 0
	global_load_lds_dwordx4 v219, s[10:11]
	s_mov_b32 m0, s95
	s_nop 0
	global_load_lds_dwordx4 v216, s[16:17]
	s_mov_b32 m0, s37
	s_nop 0
	global_load_lds_dwordx4 v218, s[16:17]
	s_add_u32 s10, s14, 0x40080
	s_addc_u32 s11, s15, 0
	s_mov_b32 m0, s56
	s_nop 0
	global_load_lds_dwordx4 v216, s[10:11]
	s_mov_b32 m0, s57
	s_nop 0
	global_load_lds_dwordx4 v218, s[10:11]
	s_waitcnt vmcnt(8)
	s_waitcnt lgkmcnt(0)
	s_cmp_eq_u32 s69, 12
	s_cbranch_scc0 .Lcw_skip
	s_cmp_eq_u64 s[4:5], 0
	s_cbranch_scc1 .Lssq_dma
	v_lshlrev_b32_e32 v242, 4, v215
	v_add3_u32 v242, v214, s59, v242
	s_lshr_b32 s32, s59, 6
	s_mul_i32 s98, s32, 0x5800
	s_add_u32 s98, s0, s98
	s_addc_u32 s99, s1, 0
	s_cmp_lt_u32 s32, 3
	s_cselect_b32 s98, s98, s2
	s_cselect_b32 s99, s99, s3
	s_lshl_b32 s32, s67, 9
	s_add_u32 s98, s98, s32
	s_addc_u32 s99, s99, 0
	v_bfe_u32 v243, v242, 5, 1
	v_mul_u32_u24_e32 v243, 0x2c00, v243
	v_and_b32_e32 v244, 31, v242
	v_lshl_add_u32 v243, v244, 4, v243
	v_readlane_b32 s32, v252, 44
	s_nop 3
	s_lshl_b32 m0, s59, 4
	s_add_u32 m0, m0, s32
	s_nop 0
	global_load_lds_dwordx4 v243, s[98:99]
	s_branch .Lcw_skip

; #define PG8_WAIT_V(n) asm volatile("s_waitcnt vmcnt(" #n ")" ::: "memory")
; #define PG8_WAIT_L(n) asm volatile("s_waitcnt lgkmcnt(" #n ")" ::: "memory")
; #define PG8_BAR __builtin_amdgcn_s_barrier()
; #define PG8_SCHED __builtin_amdgcn_sched_barrier(0)
; template <class Epi>
; __device__ __forceinline__ void gemm_phase(LAS unsigned char* lds, const Gemm g, const StaticOrder& S, const Epi& E) {
;     ...
;             PG8_WAIT_V(8); PG8_WAIT_L(0); PG8_BAR; PG8_MMA2B(1, At, At2, B0); PG8_BAR; PG8_SCHED;
;         }
;         if (wr == 0) PG8_BAR;
;     __device__ __forceinline__ void operator()(f32x4 (&acc)[2][2][4][2], const Unit& u, int wr, int wc, int fr, int fq) const {
;     ...
;           if (wr == 0) { const float* sp = ssq + ((size_t)u.pm * 256 + t) * 16; const f32x4 a = *(const f32x4*)sp, b = *(const f32x4*)(sp + 4), c = *(const f32x4*)(sp + 8), d = *(const f32x4*)(sp + 12);
;               const f32x4 q = (a + b) + (c + d); rsL[t] = rsqrtf(((q[0] + q[1]) + (q[2] + q[3])) * (1.0f / 1024.0f) + EPS); }
.Lcw_skip:
	s_barrier
	v_mfma_f32_16x16x32_bf16 v[72:75], v[68:71], v[132:135], v[72:75]
	v_mfma_f32_16x16x32_bf16 v[56:59], v[88:91], v[132:135], v[56:59]
	v_mfma_f32_16x16x32_bf16 v[96:99], v[68:71], v[152:155], v[96:99]
	v_mfma_f32_16x16x32_bf16 v[72:75], v[84:87], v[140:143], v[72:75]
	v_mfma_f32_16x16x32_bf16 v[56:59], v[92:95], v[140:143], v[56:59]
	v_mfma_f32_16x16x32_bf16 v[140:143], v[84:87], v[156:159], v[96:99]
	v_mfma_f32_16x16x32_bf16 v[96:99], v[68:71], v[166:169], v[100:103]
	v_mfma_f32_16x16x32_bf16 v[132:135], v[84:87], v[178:181], v[96:99]
	v_mfma_f32_16x16x32_bf16 v[96:99], v[68:71], v[182:185], v[128:131]
	v_mfma_f32_16x16x32_bf16 v[128:131], v[84:87], v[186:189], v[96:99]
	v_mfma_f32_16x16x32_bf16 v[96:99], v[68:71], v[190:193], v[116:119]
	v_mfma_f32_16x16x32_bf16 v[116:119], v[84:87], v[194:197], v[96:99]
	v_mfma_f32_16x16x32_bf16 v[96:99], v[68:71], v[198:201], v[108:111]
	v_mfma_f32_16x16x32_bf16 v[44:47], v[88:91], v[152:155], v[44:47]
	v_mfma_f32_16x16x32_bf16 v[36:39], v[88:91], v[166:169], v[36:39]
	v_mfma_f32_16x16x32_bf16 v[32:35], v[88:91], v[182:185], v[32:35]
	v_mfma_f32_16x16x32_bf16 v[20:23], v[88:91], v[190:193], v[20:23]
	v_mfma_f32_16x16x32_bf16 v[108:111], v[84:87], v[202:205], v[96:99]
	v_mfma_f32_16x16x32_bf16 v[12:15], v[88:91], v[198:201], v[12:15]
	v_mfma_f32_16x16x32_bf16 v[96:99], v[68:71], v[226:229], v[104:107]
	v_mfma_f32_16x16x32_bf16 v[8:11], v[88:91], v[226:229], v[8:11]
	v_mfma_f32_16x16x32_bf16 v[60:63], v[68:71], v[234:237], v[60:63]
	v_mfma_f32_16x16x32_bf16 v[0:3], v[88:91], v[234:237], v[0:3]
	v_mfma_f32_16x16x32_bf16 v[44:47], v[92:95], v[156:159], v[44:47]
	v_mfma_f32_16x16x32_bf16 v[36:39], v[92:95], v[178:181], v[36:39]
	v_mfma_f32_16x16x32_bf16 v[32:35], v[92:95], v[186:189], v[32:35]
	v_mfma_f32_16x16x32_bf16 v[20:23], v[92:95], v[194:197], v[20:23]
	v_mfma_f32_16x16x32_bf16 v[12:15], v[92:95], v[202:205], v[12:15]
	v_mfma_f32_16x16x32_bf16 v[104:107], v[84:87], v[230:233], v[96:99]
	v_mfma_f32_16x16x32_bf16 v[8:11], v[92:95], v[230:233], v[8:11]
	v_mfma_f32_16x16x32_bf16 v[60:63], v[84:87], v[238:241], v[60:63]
	v_mfma_f32_16x16x32_bf16 v[0:3], v[92:95], v[238:241], v[0:3]
	s_barrier
	s_add_i32 s69, s69, 2
	s_add_u32 vcc_hi, vcc_hi, 0x100
	s_addc_u32 s68, s68, 0
	s_cmp_gt_u32 s69, 13
	s_mov_b64 s[10:11], s[12:13]
	s_cbranch_scc0 .LBB0_1027
	s_and_b64 vcc, exec, s[90:91]
	s_cbranch_vccz .LBB0_1030
	s_barrier
